# attention diagonal steps hand-written: per sub-tile wave-uniform dispatch (past -> unmasked scheduled body, diagonal -> 2-VALU-per-element mask, future -> skip)
# speedup vs baseline: 1.0056x; 1.0008x over previous
.LBB0_107:
	s_cmp_lt_u32 s42, s98
	s_cbranch_scc1 .Lnd_107
	s_and_b32 s33, s42, 1
	s_mul_i32 s6, s33, 0x9000
	v_add_u32_e32 v199, s6, v187
	v_add_u32_e32 v198, s6, v188
	s_mov_b64 s[54:55], exec
	v_readfirstlane_b32 s32, v195
	s_sub_i32 s32, s32, 31
	s_add_i32 s4, s97, 0
	s_cmp_gt_i32 s4, s32
	s_cbranch_scc1 .Lmk_skip0
	s_cmp_eq_u32 s4, s32
	s_cbranch_scc1 .Lmk_diag0
	ds_read_b128 v[216:219], v199 offset:0
	ds_read_b128 v[232:235], v193 offset:0
	ds_read_b128 v[220:223], v199 offset:32
	ds_read_b128 v[236:239], v193 offset:32
	ds_read_b128 v[224:227], v199 offset:64
	ds_read_b128 v[244:247], v193 offset:64
	ds_read_b128 v[228:231], v199 offset:96
	ds_read_b128 v[248:251], v193 offset:96
	s_waitcnt lgkmcnt(6)
	v_mfma_f32_32x32x16_bf16 v[144:159], v[216:219], v[232:235], v[0:15]
	s_waitcnt lgkmcnt(4)
	v_mfma_f32_32x32x16_bf16 v[144:159], v[220:223], v[236:239], v[144:159]
	s_waitcnt lgkmcnt(2)
	v_mfma_f32_32x32x16_bf16 v[144:159], v[224:227], v[244:247], v[144:159]
	s_waitcnt lgkmcnt(0)
	v_mfma_f32_32x32x16_bf16 v[144:159], v[228:231], v[248:251], v[144:159]
	ds_read_b128 v[216:219], v199 offset:9216
	ds_read_b128 v[232:235], v193 offset:36864
	ds_read_b128 v[220:223], v199 offset:9248
	ds_read_b128 v[236:239], v193 offset:36896
	ds_read_b128 v[224:227], v199 offset:9280
	ds_read_b128 v[244:247], v193 offset:36928
	ds_read_b128 v[228:231], v199 offset:9312
	ds_read_b128 v[248:251], v193 offset:36960
	s_nop 3
	v_exp_f32_e32 v144, v144
	v_exp_f32_e32 v145, v145
	v_exp_f32_e32 v146, v146
	v_add_f32_e32 v243, v144, v145
	v_exp_f32_e32 v147, v147
	v_add_f32_e32 v243, v146, v243
	v_exp_f32_e32 v148, v148
	v_add_f32_e32 v243, v147, v243
	v_exp_f32_e32 v149, v149
	v_add_f32_e32 v243, v148, v243
	v_exp_f32_e32 v150, v150
	v_add_f32_e32 v243, v149, v243
	v_exp_f32_e32 v151, v151
	v_add_f32_e32 v243, v150, v243
	v_exp_f32_e32 v152, v152
	v_add_f32_e32 v243, v151, v243
	v_exp_f32_e32 v153, v153
	v_add_f32_e32 v243, v152, v243
	v_exp_f32_e32 v154, v154
	v_add_f32_e32 v243, v153, v243
	v_exp_f32_e32 v155, v155
	v_add_f32_e32 v243, v154, v243
	v_exp_f32_e32 v156, v156
	v_add_f32_e32 v243, v155, v243
	s_waitcnt lgkmcnt(6)
	v_mfma_f32_32x32x16_bf16 v[200:215], v[216:219], v[232:235], v[0:15]
	v_exp_f32_e32 v157, v157
	v_add_f32_e32 v243, v156, v243
	v_exp_f32_e32 v158, v158
	v_add_f32_e32 v243, v157, v243
	s_waitcnt lgkmcnt(4)
	v_mfma_f32_32x32x16_bf16 v[200:215], v[220:223], v[236:239], v[200:215]
	v_exp_f32_e32 v159, v159
	v_add_f32_e32 v243, v158, v243
	v_add_f32_e32 v243, v159, v243
	v_add_f32_e32 v196, v196, v243
	s_waitcnt lgkmcnt(2)
	v_mfma_f32_32x32x16_bf16 v[200:215], v[224:227], v[244:247], v[200:215]
	v_cvt_pk_bf16_f32 v144, v144, v145
	v_cvt_pk_bf16_f32 v145, v146, v147
	v_cvt_pk_bf16_f32 v146, v148, v149
	v_cvt_pk_bf16_f32 v147, v150, v151
	s_waitcnt lgkmcnt(0)
	v_mfma_f32_32x32x16_bf16 v[200:215], v[228:231], v[248:251], v[200:215]
	ds_read_b128 v[216:219], v198 offset:0
	ds_read_b128 v[224:227], v198 offset:4608
	ds_read_b128 v[232:235], v198 offset:9216
	ds_read_b128 v[244:247], v198 offset:13824
	ds_read_b128 v[220:223], v198 offset:32
	ds_read_b128 v[228:231], v198 offset:4640
	ds_read_b128 v[236:239], v198 offset:9248
	ds_read_b128 v[248:251], v198 offset:13856
	v_cvt_pk_bf16_f32 v148, v152, v153
	v_cvt_pk_bf16_f32 v149, v154, v155
	v_cvt_pk_bf16_f32 v150, v156, v157
	v_cvt_pk_bf16_f32 v151, v158, v159
	s_waitcnt lgkmcnt(7)
	v_mfma_f32_32x32x16_bf16 v[112:127], v[216:219], v[144:147], v[112:127]
	v_exp_f32_e32 v200, v200
	v_exp_f32_e32 v201, v201
	v_exp_f32_e32 v202, v202
	v_add_f32_e32 v243, v200, v201
	v_exp_f32_e32 v203, v203
	s_waitcnt lgkmcnt(6)
	v_mfma_f32_32x32x16_bf16 v[80:95], v[224:227], v[144:147], v[80:95]
	v_add_f32_e32 v243, v202, v243
	v_exp_f32_e32 v204, v204
	v_add_f32_e32 v243, v203, v243
	v_exp_f32_e32 v205, v205
	v_add_f32_e32 v243, v204, v243
	s_waitcnt lgkmcnt(5)
	v_mfma_f32_32x32x16_bf16 v[48:63], v[232:235], v[144:147], v[48:63]
	v_exp_f32_e32 v206, v206
	v_add_f32_e32 v243, v205, v243
	v_exp_f32_e32 v207, v207
	v_add_f32_e32 v243, v206, v243
	v_exp_f32_e32 v208, v208
	s_waitcnt lgkmcnt(4)
	v_mfma_f32_32x32x16_bf16 v[16:31], v[244:247], v[144:147], v[16:31]
	v_add_f32_e32 v243, v207, v243
	v_exp_f32_e32 v209, v209
	v_add_f32_e32 v243, v208, v243
	v_exp_f32_e32 v210, v210
	v_add_f32_e32 v243, v209, v243
	s_waitcnt lgkmcnt(3)
	v_mfma_f32_32x32x16_bf16 v[112:127], v[220:223], v[148:151], v[112:127]
	v_exp_f32_e32 v211, v211
	v_add_f32_e32 v243, v210, v243
	v_exp_f32_e32 v212, v212
	v_add_f32_e32 v243, v211, v243
	v_exp_f32_e32 v213, v213
	s_waitcnt lgkmcnt(2)
	v_mfma_f32_32x32x16_bf16 v[80:95], v[228:231], v[148:151], v[80:95]
	v_add_f32_e32 v243, v212, v243
	v_exp_f32_e32 v214, v214
	v_add_f32_e32 v243, v213, v243
	v_exp_f32_e32 v215, v215
	v_add_f32_e32 v243, v214, v243
	s_waitcnt lgkmcnt(1)
	v_mfma_f32_32x32x16_bf16 v[48:63], v[236:239], v[148:151], v[48:63]
	v_add_f32_e32 v243, v215, v243
	v_add_f32_e32 v197, v197, v243
	v_cvt_pk_bf16_f32 v200, v200, v201
	v_cvt_pk_bf16_f32 v201, v202, v203
	v_cvt_pk_bf16_f32 v202, v204, v205
	s_waitcnt lgkmcnt(0)
	v_mfma_f32_32x32x16_bf16 v[16:31], v[248:251], v[148:151], v[16:31]
	v_cvt_pk_bf16_f32 v203, v206, v207
	v_cvt_pk_bf16_f32 v204, v208, v209
	v_cvt_pk_bf16_f32 v205, v210, v211
	v_cvt_pk_bf16_f32 v206, v212, v213
	v_cvt_pk_bf16_f32 v207, v214, v215
	s_nop 1
	v_mfma_f32_32x32x16_bf16 v[128:143], v[216:219], v[200:203], v[128:143]
	v_mfma_f32_32x32x16_bf16 v[96:111], v[224:227], v[200:203], v[96:111]
	v_mfma_f32_32x32x16_bf16 v[64:79], v[232:235], v[200:203], v[64:79]
	v_mfma_f32_32x32x16_bf16 v[32:47], v[244:247], v[200:203], v[32:47]
	v_mfma_f32_32x32x16_bf16 v[128:143], v[220:223], v[204:207], v[128:143]
	v_mfma_f32_32x32x16_bf16 v[96:111], v[228:231], v[204:207], v[96:111]
	v_mfma_f32_32x32x16_bf16 v[64:79], v[236:239], v[204:207], v[64:79]
	v_mfma_f32_32x32x16_bf16 v[32:47], v[248:251], v[204:207], v[32:47]
	s_branch .Lmk_skip0
.Lmk_diag0:
	v_and_b32_e32 v252, 63, v186
	v_lshrrev_b32_e32 v253, 5, v252
	v_and_b32_e32 v252, 31, v252
	v_lshlrev_b32_e32 v253, 2, v253
	v_sub_u32_e32 v252, v252, v253
	v_cmp_ge_i32_e64 s[4:5], v252, 0
	v_cmp_ge_i32_e64 s[6:7], v252, 1
	v_cmp_ge_i32_e64 s[8:9], v252, 2
	v_cmp_ge_i32_e64 s[10:11], v252, 3
	v_cmp_ge_i32_e64 s[12:13], v252, 8
	v_cmp_ge_i32_e64 s[14:15], v252, 9
	v_cmp_ge_i32_e64 s[16:17], v252, 10
	v_cmp_ge_i32_e64 s[18:19], v252, 11
	v_cmp_ge_i32_e64 s[20:21], v252, 16
	v_cmp_ge_i32_e64 s[22:23], v252, 17
	v_cmp_ge_i32_e64 s[24:25], v252, 18
	v_cmp_ge_i32_e64 s[26:27], v252, 19
	v_cmp_ge_i32_e64 s[28:29], v252, 24
	v_cmp_ge_i32_e64 s[30:31], v252, 25
	v_cmp_ge_i32_e64 s[34:35], v252, 26
	v_cmp_ge_i32_e64 s[36:37], v252, 27
	ds_read_b128 v[216:219], v199 offset:0
	ds_read_b128 v[232:235], v193 offset:0
	ds_read_b128 v[220:223], v199 offset:32
	ds_read_b128 v[236:239], v193 offset:32
	ds_read_b128 v[224:227], v199 offset:64
	ds_read_b128 v[244:247], v193 offset:64
	ds_read_b128 v[228:231], v199 offset:96
	ds_read_b128 v[248:251], v193 offset:96
	s_waitcnt lgkmcnt(6)
	v_mfma_f32_32x32x16_bf16 v[144:159], v[216:219], v[232:235], v[0:15]
	s_waitcnt lgkmcnt(4)
	v_mfma_f32_32x32x16_bf16 v[144:159], v[220:223], v[236:239], v[144:159]
	s_waitcnt lgkmcnt(2)
	v_mfma_f32_32x32x16_bf16 v[144:159], v[224:227], v[244:247], v[144:159]
	s_waitcnt lgkmcnt(0)
	v_mfma_f32_32x32x16_bf16 v[144:159], v[228:231], v[248:251], v[144:159]
	ds_read_b128 v[216:219], v199 offset:9216
	ds_read_b128 v[232:235], v193 offset:36864
	ds_read_b128 v[220:223], v199 offset:9248
	ds_read_b128 v[236:239], v193 offset:36896
	ds_read_b128 v[224:227], v199 offset:9280
	ds_read_b128 v[244:247], v193 offset:36928
	ds_read_b128 v[228:231], v199 offset:9312
	ds_read_b128 v[248:251], v193 offset:36960
	s_nop 3
	v_exp_f32_e32 v144, v144
	v_exp_f32_e32 v145, v145
	v_exp_f32_e32 v146, v146
	v_exp_f32_e32 v147, v147
	v_exp_f32_e32 v148, v148
	v_exp_f32_e32 v149, v149
	v_exp_f32_e32 v150, v150
	v_exp_f32_e32 v151, v151
	v_exp_f32_e32 v152, v152
	v_exp_f32_e32 v153, v153
	v_exp_f32_e32 v154, v154
	v_exp_f32_e32 v155, v155
	v_exp_f32_e32 v156, v156
	v_exp_f32_e32 v157, v157
	v_exp_f32_e32 v158, v158
	v_exp_f32_e32 v159, v159
	v_cndmask_b32_e64 v144, 0, v144, s[4:5]
	v_cndmask_b32_e64 v145, 0, v145, s[6:7]
	v_cndmask_b32_e64 v146, 0, v146, s[8:9]
	v_cndmask_b32_e64 v147, 0, v147, s[10:11]
	v_cndmask_b32_e64 v148, 0, v148, s[12:13]
	v_cndmask_b32_e64 v149, 0, v149, s[14:15]
	v_cndmask_b32_e64 v150, 0, v150, s[16:17]
	v_cndmask_b32_e64 v151, 0, v151, s[18:19]
	v_cndmask_b32_e64 v152, 0, v152, s[20:21]
	v_cndmask_b32_e64 v153, 0, v153, s[22:23]
	v_cndmask_b32_e64 v154, 0, v154, s[24:25]
	v_cndmask_b32_e64 v155, 0, v155, s[26:27]
	v_cndmask_b32_e64 v156, 0, v156, s[28:29]
	v_cndmask_b32_e64 v157, 0, v157, s[30:31]
	v_cndmask_b32_e64 v158, 0, v158, s[34:35]
	v_cndmask_b32_e64 v159, 0, v159, s[36:37]
	v_add_f32_e32 v243, v144, v145
	v_add_f32_e32 v243, v146, v243
	v_add_f32_e32 v243, v147, v243
	v_add_f32_e32 v243, v148, v243
	v_add_f32_e32 v243, v149, v243
	v_add_f32_e32 v243, v150, v243
	v_add_f32_e32 v243, v151, v243
	v_add_f32_e32 v243, v152, v243
	v_add_f32_e32 v243, v153, v243
	v_add_f32_e32 v243, v154, v243
	v_add_f32_e32 v243, v155, v243
	v_add_f32_e32 v243, v156, v243
	v_add_f32_e32 v243, v157, v243
	v_add_f32_e32 v243, v158, v243
	v_add_f32_e32 v243, v159, v243
	v_add_f32_e32 v196, v196, v243
	v_cvt_pk_bf16_f32 v144, v144, v145
	v_cvt_pk_bf16_f32 v145, v146, v147
	v_cvt_pk_bf16_f32 v146, v148, v149
	v_cvt_pk_bf16_f32 v147, v150, v151
	v_cvt_pk_bf16_f32 v148, v152, v153
	v_cvt_pk_bf16_f32 v149, v154, v155
	v_cvt_pk_bf16_f32 v150, v156, v157
	v_cvt_pk_bf16_f32 v151, v158, v159
	s_waitcnt lgkmcnt(6)
	v_mfma_f32_32x32x16_bf16 v[200:215], v[216:219], v[232:235], v[0:15]
	s_waitcnt lgkmcnt(4)
	v_mfma_f32_32x32x16_bf16 v[200:215], v[220:223], v[236:239], v[200:215]
	s_waitcnt lgkmcnt(2)
	v_mfma_f32_32x32x16_bf16 v[200:215], v[224:227], v[244:247], v[200:215]
	s_waitcnt lgkmcnt(0)
	v_mfma_f32_32x32x16_bf16 v[200:215], v[228:231], v[248:251], v[200:215]
	ds_read_b128 v[216:219], v198 offset:0
	ds_read_b128 v[224:227], v198 offset:4608
	ds_read_b128 v[232:235], v198 offset:9216
	ds_read_b128 v[244:247], v198 offset:13824
	ds_read_b128 v[220:223], v198 offset:32
	ds_read_b128 v[228:231], v198 offset:4640
	ds_read_b128 v[236:239], v198 offset:9248
	ds_read_b128 v[248:251], v198 offset:13856
	s_nop 3
	v_exp_f32_e32 v200, v200
	v_exp_f32_e32 v201, v201
	v_exp_f32_e32 v202, v202
	v_exp_f32_e32 v203, v203
	v_exp_f32_e32 v204, v204
	v_exp_f32_e32 v205, v205
	v_exp_f32_e32 v206, v206
	v_exp_f32_e32 v207, v207
	v_exp_f32_e32 v208, v208
	v_exp_f32_e32 v209, v209
	v_exp_f32_e32 v210, v210
	v_exp_f32_e32 v211, v211
	v_exp_f32_e32 v212, v212
	v_exp_f32_e32 v213, v213
	v_exp_f32_e32 v214, v214
	v_exp_f32_e32 v215, v215
	v_cndmask_b32_e64 v200, 0, v200, s[4:5]
	v_cndmask_b32_e64 v201, 0, v201, s[6:7]
	v_cndmask_b32_e64 v202, 0, v202, s[8:9]
	v_cndmask_b32_e64 v203, 0, v203, s[10:11]
	v_cndmask_b32_e64 v204, 0, v204, s[12:13]
	v_cndmask_b32_e64 v205, 0, v205, s[14:15]
	v_cndmask_b32_e64 v206, 0, v206, s[16:17]
	v_cndmask_b32_e64 v207, 0, v207, s[18:19]
	v_cndmask_b32_e64 v208, 0, v208, s[20:21]
	v_cndmask_b32_e64 v209, 0, v209, s[22:23]
	v_cndmask_b32_e64 v210, 0, v210, s[24:25]
	v_cndmask_b32_e64 v211, 0, v211, s[26:27]
	v_cndmask_b32_e64 v212, 0, v212, s[28:29]
	v_cndmask_b32_e64 v213, 0, v213, s[30:31]
	v_cndmask_b32_e64 v214, 0, v214, s[34:35]
	v_cndmask_b32_e64 v215, 0, v215, s[36:37]
	v_add_f32_e32 v243, v200, v201
	v_add_f32_e32 v243, v202, v243
	v_add_f32_e32 v243, v203, v243
	v_add_f32_e32 v243, v204, v243
	v_add_f32_e32 v243, v205, v243
	v_add_f32_e32 v243, v206, v243
	v_add_f32_e32 v243, v207, v243
	v_add_f32_e32 v243, v208, v243
	v_add_f32_e32 v243, v209, v243
	v_add_f32_e32 v243, v210, v243
	v_add_f32_e32 v243, v211, v243
	v_add_f32_e32 v243, v212, v243
	v_add_f32_e32 v243, v213, v243
	v_add_f32_e32 v243, v214, v243
	v_add_f32_e32 v243, v215, v243
	v_add_f32_e32 v197, v197, v243
	v_cvt_pk_bf16_f32 v200, v200, v201
	v_cvt_pk_bf16_f32 v201, v202, v203
	v_cvt_pk_bf16_f32 v202, v204, v205
	v_cvt_pk_bf16_f32 v203, v206, v207
	v_cvt_pk_bf16_f32 v204, v208, v209
	v_cvt_pk_bf16_f32 v205, v210, v211
	v_cvt_pk_bf16_f32 v206, v212, v213
	v_cvt_pk_bf16_f32 v207, v214, v215
	s_nop 1
	s_waitcnt lgkmcnt(7)
	v_mfma_f32_32x32x16_bf16 v[112:127], v[216:219], v[144:147], v[112:127]
	s_waitcnt lgkmcnt(6)
	v_mfma_f32_32x32x16_bf16 v[80:95], v[224:227], v[144:147], v[80:95]
	s_waitcnt lgkmcnt(5)
	v_mfma_f32_32x32x16_bf16 v[48:63], v[232:235], v[144:147], v[48:63]
	s_waitcnt lgkmcnt(4)
	v_mfma_f32_32x32x16_bf16 v[16:31], v[244:247], v[144:147], v[16:31]
	s_waitcnt lgkmcnt(3)
	v_mfma_f32_32x32x16_bf16 v[112:127], v[220:223], v[148:151], v[112:127]
	s_waitcnt lgkmcnt(2)
	v_mfma_f32_32x32x16_bf16 v[80:95], v[228:231], v[148:151], v[80:95]
	s_waitcnt lgkmcnt(1)
	v_mfma_f32_32x32x16_bf16 v[48:63], v[236:239], v[148:151], v[48:63]
	s_waitcnt lgkmcnt(0)
	v_mfma_f32_32x32x16_bf16 v[16:31], v[248:251], v[148:151], v[16:31]
	v_mfma_f32_32x32x16_bf16 v[128:143], v[216:219], v[200:203], v[128:143]
	v_mfma_f32_32x32x16_bf16 v[96:111], v[224:227], v[200:203], v[96:111]
	v_mfma_f32_32x32x16_bf16 v[64:79], v[232:235], v[200:203], v[64:79]
	v_mfma_f32_32x32x16_bf16 v[32:47], v[244:247], v[200:203], v[32:47]
	v_mfma_f32_32x32x16_bf16 v[128:143], v[220:223], v[204:207], v[128:143]
	v_mfma_f32_32x32x16_bf16 v[96:111], v[228:231], v[204:207], v[96:111]
	v_mfma_f32_32x32x16_bf16 v[64:79], v[236:239], v[204:207], v[64:79]
	v_mfma_f32_32x32x16_bf16 v[32:47], v[248:251], v[204:207], v[32:47]
.Lmk_skip0:
	s_add_i32 s4, s97, 32
	s_cmp_gt_i32 s4, s32
	s_cbranch_scc1 .Lmk_skip1
	s_cmp_eq_u32 s4, s32
	s_cbranch_scc1 .Lmk_diag1
	ds_read_b128 v[216:219], v199 offset:4608
	ds_read_b128 v[232:235], v193 offset:0
	ds_read_b128 v[220:223], v199 offset:4640
	ds_read_b128 v[236:239], v193 offset:32
	ds_read_b128 v[224:227], v199 offset:4672
	ds_read_b128 v[244:247], v193 offset:64
	ds_read_b128 v[228:231], v199 offset:4704
	ds_read_b128 v[248:251], v193 offset:96
	s_waitcnt lgkmcnt(6)
	v_mfma_f32_32x32x16_bf16 v[144:159], v[216:219], v[232:235], v[0:15]
	s_waitcnt lgkmcnt(4)
	v_mfma_f32_32x32x16_bf16 v[144:159], v[220:223], v[236:239], v[144:159]
	s_waitcnt lgkmcnt(2)
	v_mfma_f32_32x32x16_bf16 v[144:159], v[224:227], v[244:247], v[144:159]
	s_waitcnt lgkmcnt(0)
	v_mfma_f32_32x32x16_bf16 v[144:159], v[228:231], v[248:251], v[144:159]
	ds_read_b128 v[216:219], v199 offset:13824
	ds_read_b128 v[232:235], v193 offset:36864
	ds_read_b128 v[220:223], v199 offset:13856
	ds_read_b128 v[236:239], v193 offset:36896
	ds_read_b128 v[224:227], v199 offset:13888
	ds_read_b128 v[244:247], v193 offset:36928
	ds_read_b128 v[228:231], v199 offset:13920
	ds_read_b128 v[248:251], v193 offset:36960
	s_nop 3
	v_exp_f32_e32 v144, v144
	v_exp_f32_e32 v145, v145
	v_exp_f32_e32 v146, v146
	v_add_f32_e32 v243, v144, v145
	v_exp_f32_e32 v147, v147
	v_add_f32_e32 v243, v146, v243
	v_exp_f32_e32 v148, v148
	v_add_f32_e32 v243, v147, v243
	v_exp_f32_e32 v149, v149
	v_add_f32_e32 v243, v148, v243
	v_exp_f32_e32 v150, v150
	v_add_f32_e32 v243, v149, v243
	v_exp_f32_e32 v151, v151
	v_add_f32_e32 v243, v150, v243
	v_exp_f32_e32 v152, v152
	v_add_f32_e32 v243, v151, v243
	v_exp_f32_e32 v153, v153
	v_add_f32_e32 v243, v152, v243
	v_exp_f32_e32 v154, v154
	v_add_f32_e32 v243, v153, v243
	v_exp_f32_e32 v155, v155
	v_add_f32_e32 v243, v154, v243
	v_exp_f32_e32 v156, v156
	v_add_f32_e32 v243, v155, v243
	s_waitcnt lgkmcnt(6)
	v_mfma_f32_32x32x16_bf16 v[200:215], v[216:219], v[232:235], v[0:15]
	v_exp_f32_e32 v157, v157
	v_add_f32_e32 v243, v156, v243
	v_exp_f32_e32 v158, v158
	v_add_f32_e32 v243, v157, v243
	s_waitcnt lgkmcnt(4)
	v_mfma_f32_32x32x16_bf16 v[200:215], v[220:223], v[236:239], v[200:215]
	v_exp_f32_e32 v159, v159
	v_add_f32_e32 v243, v158, v243
	v_add_f32_e32 v243, v159, v243
	v_add_f32_e32 v196, v196, v243
	s_waitcnt lgkmcnt(2)
	v_mfma_f32_32x32x16_bf16 v[200:215], v[224:227], v[244:247], v[200:215]
	v_cvt_pk_bf16_f32 v144, v144, v145
	v_cvt_pk_bf16_f32 v145, v146, v147
	v_cvt_pk_bf16_f32 v146, v148, v149
	v_cvt_pk_bf16_f32 v147, v150, v151
	s_waitcnt lgkmcnt(0)
	v_mfma_f32_32x32x16_bf16 v[200:215], v[228:231], v[248:251], v[200:215]
	ds_read_b128 v[216:219], v198 offset:64
	ds_read_b128 v[224:227], v198 offset:4672
	ds_read_b128 v[232:235], v198 offset:9280
	ds_read_b128 v[244:247], v198 offset:13888
	ds_read_b128 v[220:223], v198 offset:96
	ds_read_b128 v[228:231], v198 offset:4704
	ds_read_b128 v[236:239], v198 offset:9312
	ds_read_b128 v[248:251], v198 offset:13920
	v_cvt_pk_bf16_f32 v148, v152, v153
	v_cvt_pk_bf16_f32 v149, v154, v155
	v_cvt_pk_bf16_f32 v150, v156, v157
	v_cvt_pk_bf16_f32 v151, v158, v159
	s_waitcnt lgkmcnt(7)
	v_mfma_f32_32x32x16_bf16 v[112:127], v[216:219], v[144:147], v[112:127]
	v_exp_f32_e32 v200, v200
	v_exp_f32_e32 v201, v201
	v_exp_f32_e32 v202, v202
	v_add_f32_e32 v243, v200, v201
	v_exp_f32_e32 v203, v203
	s_waitcnt lgkmcnt(6)
	v_mfma_f32_32x32x16_bf16 v[80:95], v[224:227], v[144:147], v[80:95]
	v_add_f32_e32 v243, v202, v243
	v_exp_f32_e32 v204, v204
	v_add_f32_e32 v243, v203, v243
	v_exp_f32_e32 v205, v205
	v_add_f32_e32 v243, v204, v243
	s_waitcnt lgkmcnt(5)
	v_mfma_f32_32x32x16_bf16 v[48:63], v[232:235], v[144:147], v[48:63]
	v_exp_f32_e32 v206, v206
	v_add_f32_e32 v243, v205, v243
	v_exp_f32_e32 v207, v207
	v_add_f32_e32 v243, v206, v243
	v_exp_f32_e32 v208, v208
	s_waitcnt lgkmcnt(4)
	v_mfma_f32_32x32x16_bf16 v[16:31], v[244:247], v[144:147], v[16:31]
	v_add_f32_e32 v243, v207, v243
	v_exp_f32_e32 v209, v209
	v_add_f32_e32 v243, v208, v243
	v_exp_f32_e32 v210, v210
	v_add_f32_e32 v243, v209, v243
	s_waitcnt lgkmcnt(3)
	v_mfma_f32_32x32x16_bf16 v[112:127], v[220:223], v[148:151], v[112:127]
	v_exp_f32_e32 v211, v211
	v_add_f32_e32 v243, v210, v243
	v_exp_f32_e32 v212, v212
	v_add_f32_e32 v243, v211, v243
	v_exp_f32_e32 v213, v213
	s_waitcnt lgkmcnt(2)
	v_mfma_f32_32x32x16_bf16 v[80:95], v[228:231], v[148:151], v[80:95]
	v_add_f32_e32 v243, v212, v243
	v_exp_f32_e32 v214, v214
	v_add_f32_e32 v243, v213, v243
	v_exp_f32_e32 v215, v215
	v_add_f32_e32 v243, v214, v243
	s_waitcnt lgkmcnt(1)
	v_mfma_f32_32x32x16_bf16 v[48:63], v[236:239], v[148:151], v[48:63]
	v_add_f32_e32 v243, v215, v243
	v_add_f32_e32 v197, v197, v243
	v_cvt_pk_bf16_f32 v200, v200, v201
	v_cvt_pk_bf16_f32 v201, v202, v203
	v_cvt_pk_bf16_f32 v202, v204, v205
	s_waitcnt lgkmcnt(0)
	v_mfma_f32_32x32x16_bf16 v[16:31], v[248:251], v[148:151], v[16:31]
	v_cvt_pk_bf16_f32 v203, v206, v207
	v_cvt_pk_bf16_f32 v204, v208, v209
	v_cvt_pk_bf16_f32 v205, v210, v211
	v_cvt_pk_bf16_f32 v206, v212, v213
	v_cvt_pk_bf16_f32 v207, v214, v215
	s_nop 1
	v_mfma_f32_32x32x16_bf16 v[128:143], v[216:219], v[200:203], v[128:143]
	v_mfma_f32_32x32x16_bf16 v[96:111], v[224:227], v[200:203], v[96:111]
	v_mfma_f32_32x32x16_bf16 v[64:79], v[232:235], v[200:203], v[64:79]
	v_mfma_f32_32x32x16_bf16 v[32:47], v[244:247], v[200:203], v[32:47]
	v_mfma_f32_32x32x16_bf16 v[128:143], v[220:223], v[204:207], v[128:143]
	v_mfma_f32_32x32x16_bf16 v[96:111], v[228:231], v[204:207], v[96:111]
	v_mfma_f32_32x32x16_bf16 v[64:79], v[236:239], v[204:207], v[64:79]
	v_mfma_f32_32x32x16_bf16 v[32:47], v[248:251], v[204:207], v[32:47]
	s_branch .Lmk_skip1
.Lmk_diag1:
	v_and_b32_e32 v252, 63, v186
	v_lshrrev_b32_e32 v253, 5, v252
	v_and_b32_e32 v252, 31, v252
	v_lshlrev_b32_e32 v253, 2, v253
	v_sub_u32_e32 v252, v252, v253
	v_cmp_ge_i32_e64 s[4:5], v252, 0
	v_cmp_ge_i32_e64 s[6:7], v252, 1
	v_cmp_ge_i32_e64 s[8:9], v252, 2
	v_cmp_ge_i32_e64 s[10:11], v252, 3
	v_cmp_ge_i32_e64 s[12:13], v252, 8
	v_cmp_ge_i32_e64 s[14:15], v252, 9
	v_cmp_ge_i32_e64 s[16:17], v252, 10
	v_cmp_ge_i32_e64 s[18:19], v252, 11
	v_cmp_ge_i32_e64 s[20:21], v252, 16
	v_cmp_ge_i32_e64 s[22:23], v252, 17
	v_cmp_ge_i32_e64 s[24:25], v252, 18
	v_cmp_ge_i32_e64 s[26:27], v252, 19
	v_cmp_ge_i32_e64 s[28:29], v252, 24
	v_cmp_ge_i32_e64 s[30:31], v252, 25
	v_cmp_ge_i32_e64 s[34:35], v252, 26
	v_cmp_ge_i32_e64 s[36:37], v252, 27
	ds_read_b128 v[216:219], v199 offset:4608
	ds_read_b128 v[232:235], v193 offset:0
	ds_read_b128 v[220:223], v199 offset:4640
	ds_read_b128 v[236:239], v193 offset:32
	ds_read_b128 v[224:227], v199 offset:4672
	ds_read_b128 v[244:247], v193 offset:64
	ds_read_b128 v[228:231], v199 offset:4704
	ds_read_b128 v[248:251], v193 offset:96
	s_waitcnt lgkmcnt(6)
	v_mfma_f32_32x32x16_bf16 v[144:159], v[216:219], v[232:235], v[0:15]
	s_waitcnt lgkmcnt(4)
	v_mfma_f32_32x32x16_bf16 v[144:159], v[220:223], v[236:239], v[144:159]
	s_waitcnt lgkmcnt(2)
	v_mfma_f32_32x32x16_bf16 v[144:159], v[224:227], v[244:247], v[144:159]
	s_waitcnt lgkmcnt(0)
	v_mfma_f32_32x32x16_bf16 v[144:159], v[228:231], v[248:251], v[144:159]
	ds_read_b128 v[216:219], v199 offset:13824
	ds_read_b128 v[232:235], v193 offset:36864
	ds_read_b128 v[220:223], v199 offset:13856
	ds_read_b128 v[236:239], v193 offset:36896
	ds_read_b128 v[224:227], v199 offset:13888
	ds_read_b128 v[244:247], v193 offset:36928
	ds_read_b128 v[228:231], v199 offset:13920
	ds_read_b128 v[248:251], v193 offset:36960
	s_nop 3
	v_exp_f32_e32 v144, v144
	v_exp_f32_e32 v145, v145
	v_exp_f32_e32 v146, v146
	v_exp_f32_e32 v147, v147
	v_exp_f32_e32 v148, v148
	v_exp_f32_e32 v149, v149
	v_exp_f32_e32 v150, v150
	v_exp_f32_e32 v151, v151
	v_exp_f32_e32 v152, v152
	v_exp_f32_e32 v153, v153
	v_exp_f32_e32 v154, v154
	v_exp_f32_e32 v155, v155
	v_exp_f32_e32 v156, v156
	v_exp_f32_e32 v157, v157
	v_exp_f32_e32 v158, v158
	v_exp_f32_e32 v159, v159
	v_cndmask_b32_e64 v144, 0, v144, s[4:5]
	v_cndmask_b32_e64 v145, 0, v145, s[6:7]
	v_cndmask_b32_e64 v146, 0, v146, s[8:9]
	v_cndmask_b32_e64 v147, 0, v147, s[10:11]
	v_cndmask_b32_e64 v148, 0, v148, s[12:13]
	v_cndmask_b32_e64 v149, 0, v149, s[14:15]
	v_cndmask_b32_e64 v150, 0, v150, s[16:17]
	v_cndmask_b32_e64 v151, 0, v151, s[18:19]
	v_cndmask_b32_e64 v152, 0, v152, s[20:21]
	v_cndmask_b32_e64 v153, 0, v153, s[22:23]
	v_cndmask_b32_e64 v154, 0, v154, s[24:25]
	v_cndmask_b32_e64 v155, 0, v155, s[26:27]
	v_cndmask_b32_e64 v156, 0, v156, s[28:29]
	v_cndmask_b32_e64 v157, 0, v157, s[30:31]
	v_cndmask_b32_e64 v158, 0, v158, s[34:35]
	v_cndmask_b32_e64 v159, 0, v159, s[36:37]
	v_add_f32_e32 v243, v144, v145
	v_add_f32_e32 v243, v146, v243
	v_add_f32_e32 v243, v147, v243
	v_add_f32_e32 v243, v148, v243
	v_add_f32_e32 v243, v149, v243
	v_add_f32_e32 v243, v150, v243
	v_add_f32_e32 v243, v151, v243
	v_add_f32_e32 v243, v152, v243
	v_add_f32_e32 v243, v153, v243
	v_add_f32_e32 v243, v154, v243
	v_add_f32_e32 v243, v155, v243
	v_add_f32_e32 v243, v156, v243
	v_add_f32_e32 v243, v157, v243
	v_add_f32_e32 v243, v158, v243
	v_add_f32_e32 v243, v159, v243
	v_add_f32_e32 v196, v196, v243
	v_cvt_pk_bf16_f32 v144, v144, v145
	v_cvt_pk_bf16_f32 v145, v146, v147
	v_cvt_pk_bf16_f32 v146, v148, v149
	v_cvt_pk_bf16_f32 v147, v150, v151
	v_cvt_pk_bf16_f32 v148, v152, v153
	v_cvt_pk_bf16_f32 v149, v154, v155
	v_cvt_pk_bf16_f32 v150, v156, v157
	v_cvt_pk_bf16_f32 v151, v158, v159
	s_waitcnt lgkmcnt(6)
	v_mfma_f32_32x32x16_bf16 v[200:215], v[216:219], v[232:235], v[0:15]
	s_waitcnt lgkmcnt(4)
	v_mfma_f32_32x32x16_bf16 v[200:215], v[220:223], v[236:239], v[200:215]
	s_waitcnt lgkmcnt(2)
	v_mfma_f32_32x32x16_bf16 v[200:215], v[224:227], v[244:247], v[200:215]
	s_waitcnt lgkmcnt(0)
	v_mfma_f32_32x32x16_bf16 v[200:215], v[228:231], v[248:251], v[200:215]
	ds_read_b128 v[216:219], v198 offset:64
	ds_read_b128 v[224:227], v198 offset:4672
	ds_read_b128 v[232:235], v198 offset:9280
	ds_read_b128 v[244:247], v198 offset:13888
	ds_read_b128 v[220:223], v198 offset:96
	ds_read_b128 v[228:231], v198 offset:4704
	ds_read_b128 v[236:239], v198 offset:9312
	ds_read_b128 v[248:251], v198 offset:13920
	s_nop 3
	v_exp_f32_e32 v200, v200
	v_exp_f32_e32 v201, v201
	v_exp_f32_e32 v202, v202
	v_exp_f32_e32 v203, v203
	v_exp_f32_e32 v204, v204
	v_exp_f32_e32 v205, v205
	v_exp_f32_e32 v206, v206
	v_exp_f32_e32 v207, v207
	v_exp_f32_e32 v208, v208
	v_exp_f32_e32 v209, v209
	v_exp_f32_e32 v210, v210
	v_exp_f32_e32 v211, v211
	v_exp_f32_e32 v212, v212
	v_exp_f32_e32 v213, v213
	v_exp_f32_e32 v214, v214
	v_exp_f32_e32 v215, v215
	v_cndmask_b32_e64 v200, 0, v200, s[4:5]
	v_cndmask_b32_e64 v201, 0, v201, s[6:7]
	v_cndmask_b32_e64 v202, 0, v202, s[8:9]
	v_cndmask_b32_e64 v203, 0, v203, s[10:11]
	v_cndmask_b32_e64 v204, 0, v204, s[12:13]
	v_cndmask_b32_e64 v205, 0, v205, s[14:15]
	v_cndmask_b32_e64 v206, 0, v206, s[16:17]
	v_cndmask_b32_e64 v207, 0, v207, s[18:19]
	v_cndmask_b32_e64 v208, 0, v208, s[20:21]
	v_cndmask_b32_e64 v209, 0, v209, s[22:23]
	v_cndmask_b32_e64 v210, 0, v210, s[24:25]
	v_cndmask_b32_e64 v211, 0, v211, s[26:27]
	v_cndmask_b32_e64 v212, 0, v212, s[28:29]
	v_cndmask_b32_e64 v213, 0, v213, s[30:31]
	v_cndmask_b32_e64 v214, 0, v214, s[34:35]
	v_cndmask_b32_e64 v215, 0, v215, s[36:37]
	v_add_f32_e32 v243, v200, v201
	v_add_f32_e32 v243, v202, v243
	v_add_f32_e32 v243, v203, v243
	v_add_f32_e32 v243, v204, v243
	v_add_f32_e32 v243, v205, v243
	v_add_f32_e32 v243, v206, v243
	v_add_f32_e32 v243, v207, v243
	v_add_f32_e32 v243, v208, v243
	v_add_f32_e32 v243, v209, v243
	v_add_f32_e32 v243, v210, v243
	v_add_f32_e32 v243, v211, v243
	v_add_f32_e32 v243, v212, v243
	v_add_f32_e32 v243, v213, v243
	v_add_f32_e32 v243, v214, v243
	v_add_f32_e32 v243, v215, v243
	v_add_f32_e32 v197, v197, v243
	v_cvt_pk_bf16_f32 v200, v200, v201
	v_cvt_pk_bf16_f32 v201, v202, v203
	v_cvt_pk_bf16_f32 v202, v204, v205
	v_cvt_pk_bf16_f32 v203, v206, v207
	v_cvt_pk_bf16_f32 v204, v208, v209
	v_cvt_pk_bf16_f32 v205, v210, v211
	v_cvt_pk_bf16_f32 v206, v212, v213
	v_cvt_pk_bf16_f32 v207, v214, v215
	s_nop 1
	s_waitcnt lgkmcnt(7)
	v_mfma_f32_32x32x16_bf16 v[112:127], v[216:219], v[144:147], v[112:127]
	s_waitcnt lgkmcnt(6)
	v_mfma_f32_32x32x16_bf16 v[80:95], v[224:227], v[144:147], v[80:95]
	s_waitcnt lgkmcnt(5)
	v_mfma_f32_32x32x16_bf16 v[48:63], v[232:235], v[144:147], v[48:63]
	s_waitcnt lgkmcnt(4)
	v_mfma_f32_32x32x16_bf16 v[16:31], v[244:247], v[144:147], v[16:31]
	s_waitcnt lgkmcnt(3)
	v_mfma_f32_32x32x16_bf16 v[112:127], v[220:223], v[148:151], v[112:127]
	s_waitcnt lgkmcnt(2)
	v_mfma_f32_32x32x16_bf16 v[80:95], v[228:231], v[148:151], v[80:95]
	s_waitcnt lgkmcnt(1)
	v_mfma_f32_32x32x16_bf16 v[48:63], v[236:239], v[148:151], v[48:63]
	s_waitcnt lgkmcnt(0)
	v_mfma_f32_32x32x16_bf16 v[16:31], v[248:251], v[148:151], v[16:31]
	v_mfma_f32_32x32x16_bf16 v[128:143], v[216:219], v[200:203], v[128:143]
	v_mfma_f32_32x32x16_bf16 v[96:111], v[224:227], v[200:203], v[96:111]
	v_mfma_f32_32x32x16_bf16 v[64:79], v[232:235], v[200:203], v[64:79]
	v_mfma_f32_32x32x16_bf16 v[32:47], v[244:247], v[200:203], v[32:47]
	v_mfma_f32_32x32x16_bf16 v[128:143], v[220:223], v[204:207], v[128:143]
	v_mfma_f32_32x32x16_bf16 v[96:111], v[228:231], v[204:207], v[96:111]
	v_mfma_f32_32x32x16_bf16 v[64:79], v[236:239], v[204:207], v[64:79]
	v_mfma_f32_32x32x16_bf16 v[32:47], v[248:251], v[204:207], v[32:47]
.Lmk_skip1:
	s_branch .LBB0_111
